# phase B2 (compression MLP layer 2) k-step loads issued together instead of one round trip per pair
# speedup vs baseline: 1.0647x; 1.0141x over previous
; #define MFMA16(a, b, c) __builtin_amdgcn_mfma_f32_16x16x32_bf16((a), (b), (c), 0, 0, 0)
; DI unsigned pk2(float lo, float hi) { f32x2 v = {lo, hi}; bf16x2_t b = __builtin_convertvector(v, bf16x2_t); return __builtin_bit_cast(unsigned, b); }
; DI float siluf_(float x) { return x * __builtin_amdgcn_rcpf(1.f + __builtin_amdgcn_exp2f(-1.44269504089f * x)); }
; DI void phaseB2(const Params& p0, int layer, unsigned char* lds) {
;     ...
;     for (int ksx = 0; ksx < 8; ++ksx) {
;       f32x4 h0 = *(const f32x4*)(bias_s + kv * 256 + ksx * 32 + quad * 8), h1 = *(const f32x4*)(bias_s + kv * 256 + ksx * 32 + quad * 8 + 4);
; #pragma unroll
;       for (int sp = 0; sp < 4; ++sp) { const float* q = hp + (long)sp * 32 * 256 * 256 + ksx * 32; h0 += *(const f32x4*)q; h1 += *(const f32x4*)(q + 4); }
;       const bf16x8 hf = mk8((u32x4){pk2(siluf_(h0[0]), siluf_(h0[1])), pk2(siluf_(h0[2]), siluf_(h0[3])), pk2(siluf_(h1[0]), siluf_(h1[1])), pk2(siluf_(h1[2]), siluf_(h1[3]))});
; #pragma unroll
;       for (int dt = 0; dt < 4; ++dt) {
;         const bf16x8 wf = ld8(W2 + (long)(dt * 16 + qi) * 256 + ksx * 32 + quad * 8);
;         o[dt] = kv ? MFMA16(hf, wf, o[dt]) : MFMA16(wf, hf, o[dt]);
;       }
.LBB0_630:
	v_lshl_add_u64 v[42:43], v[38:39], 0, s[4:5]
	v_add_u32_e32 v0, s27, v37
	ds_read_b128 v[92:95], v0
	ds_read_b128 v[96:99], v0 offset:16
	s_mov_b64 s[28:29], 0x1d570000
	v_lshl_add_u64 v[56:57], v[42:43], 0, s[28:29]
	global_load_dwordx4 v[60:63], v[56:57], off
	global_load_dwordx4 v[64:67], v[56:57], off offset:16
	s_mov_b64 s[28:29], 0x1dd70000
	v_lshl_add_u64 v[56:57], v[42:43], 0, s[28:29]
	global_load_dwordx4 v[68:71], v[56:57], off
	global_load_dwordx4 v[72:75], v[56:57], off offset:16
	s_mov_b64 s[28:29], 0x1e570000
	v_lshl_add_u64 v[56:57], v[42:43], 0, s[28:29]
	global_load_dwordx4 v[76:79], v[56:57], off
	global_load_dwordx4 v[80:83], v[56:57], off offset:16
	s_mov_b64 s[28:29], 0x1ed70000
	v_lshl_add_u64 v[56:57], v[42:43], 0, s[28:29]
	global_load_dwordx4 v[84:87], v[56:57], off
	global_load_dwordx4 v[88:91], v[56:57], off offset:16
	v_lshl_add_u64 v[42:43], v[40:41], 0, s[4:5]
	s_mov_b64 s[28:29], 0xec0000
	v_lshl_add_u64 v[56:57], v[42:43], 0, s[28:29]
	global_load_dwordx4 v[100:103], v[56:57], off
	s_mov_b64 s[28:29], 0xec2000
	v_lshl_add_u64 v[56:57], v[42:43], 0, s[28:29]
	global_load_dwordx4 v[104:107], v[56:57], off
	s_mov_b64 s[28:29], 0xec4000
	v_lshl_add_u64 v[56:57], v[42:43], 0, s[28:29]
	global_load_dwordx4 v[108:111], v[56:57], off
	s_mov_b64 s[28:29], 0xec6000
	v_lshl_add_u64 v[56:57], v[42:43], 0, s[28:29]
	global_load_dwordx4 v[112:115], v[56:57], off
	s_waitcnt vmcnt(10) lgkmcnt(0)
	v_pk_add_f32 v[92:93], v[92:93], v[60:61]
	v_pk_add_f32 v[94:95], v[94:95], v[62:63]
	v_pk_add_f32 v[96:97], v[96:97], v[64:65]
	v_pk_add_f32 v[98:99], v[98:99], v[66:67]
	s_waitcnt vmcnt(8)
	v_pk_add_f32 v[92:93], v[92:93], v[68:69]
	v_pk_add_f32 v[94:95], v[94:95], v[70:71]
	v_pk_add_f32 v[96:97], v[96:97], v[72:73]
	v_pk_add_f32 v[98:99], v[98:99], v[74:75]
	s_waitcnt vmcnt(6)
	v_pk_add_f32 v[92:93], v[92:93], v[76:77]
	v_pk_add_f32 v[94:95], v[94:95], v[78:79]
	v_pk_add_f32 v[96:97], v[96:97], v[80:81]
	v_pk_add_f32 v[98:99], v[98:99], v[82:83]
	s_waitcnt vmcnt(4)
	v_pk_add_f32 v[92:93], v[92:93], v[84:85]
	v_pk_add_f32 v[94:95], v[94:95], v[86:87]
	v_pk_add_f32 v[96:97], v[96:97], v[88:89]
	v_pk_add_f32 v[98:99], v[98:99], v[90:91]
	v_mul_f32_e32 v116, 0xbfb8aa3b, v92
	v_mul_f32_e32 v117, 0xbfb8aa3b, v93
	v_mul_f32_e32 v118, 0xbfb8aa3b, v94
	v_mul_f32_e32 v119, 0xbfb8aa3b, v95
	v_mul_f32_e32 v120, 0xbfb8aa3b, v96
	v_mul_f32_e32 v121, 0xbfb8aa3b, v97
	v_mul_f32_e32 v122, 0xbfb8aa3b, v98
	v_mul_f32_e32 v123, 0xbfb8aa3b, v99
	v_exp_f32_e32 v116, v116
	v_exp_f32_e32 v117, v117
	v_exp_f32_e32 v118, v118
	v_exp_f32_e32 v119, v119
	v_exp_f32_e32 v120, v120
	v_exp_f32_e32 v121, v121
	v_exp_f32_e32 v122, v122
	v_exp_f32_e32 v123, v123
	v_add_f32_e32 v116, 1.0, v116
	v_add_f32_e32 v117, 1.0, v117
	v_add_f32_e32 v118, 1.0, v118
	v_add_f32_e32 v119, 1.0, v119
	v_add_f32_e32 v120, 1.0, v120
	v_add_f32_e32 v121, 1.0, v121
	v_add_f32_e32 v122, 1.0, v122
	v_add_f32_e32 v123, 1.0, v123
	v_rcp_f32_e32 v124, v116
	v_rcp_f32_e32 v125, v117
	v_rcp_f32_e32 v126, v118
	v_rcp_f32_e32 v127, v119
	v_rcp_f32_e32 v128, v120
	v_rcp_f32_e32 v129, v121
	v_rcp_f32_e32 v130, v122
	v_rcp_f32_e32 v131, v123
	v_pk_mul_f32 v[92:93], v[92:93], v[124:125]
	v_pk_mul_f32 v[94:95], v[94:95], v[126:127]
	v_pk_mul_f32 v[96:97], v[96:97], v[128:129]
	v_pk_mul_f32 v[98:99], v[98:99], v[130:131]
	v_cvt_pk_bf16_f32 v18, v92, v93
	v_cvt_pk_bf16_f32 v19, v94, v95
	v_cvt_pk_bf16_f32 v20, v96, v97
	v_cvt_pk_bf16_f32 v21, v98, v99
	s_waitcnt vmcnt(0)
	s_cmp_lg_u64 s[8:9], 0
	s_cbranch_scc0 .Lmy_b2_k
	v_mfma_f32_16x16x32_bf16 v[14:17], v[18:21], v[100:103], v[14:17]
	v_mfma_f32_16x16x32_bf16 v[10:13], v[18:21], v[104:107], v[10:13]
	v_mfma_f32_16x16x32_bf16 v[6:9], v[18:21], v[108:111], v[6:9]
	v_mfma_f32_16x16x32_bf16 v[2:5], v[18:21], v[112:115], v[2:5]
	s_branch .Lmy_b2_next
.Lmy_b2_k:
	v_mfma_f32_16x16x32_bf16 v[14:17], v[100:103], v[18:21], v[14:17]
	v_mfma_f32_16x16x32_bf16 v[10:13], v[104:107], v[18:21], v[10:13]
	v_mfma_f32_16x16x32_bf16 v[6:9], v[108:111], v[18:21], v[6:9]
	v_mfma_f32_16x16x32_bf16 v[2:5], v[112:115], v[18:21], v[2:5]
.Lmy_b2_next:
	s_mov_b64 s[38:39], exec
	s_branch .LBB0_629
